# spread rg-gate weight transposes over workgroups 0..79 (was all on 0..3), on top of KI relayout + radix ballots + k11 fragment double buffering
# speedup vs baseline: 1.0424x; 1.0191x over previous
.LBB0_131:
	s_lshl_b32 s56, s16, 14
	v_mov_b32_e32 v4, v192
	s_lshl_b32 s17, s16, 3
	s_sub_i32 s17, s55, s17
	s_cmp_gt_u32 s17, 3
	s_cbranch_scc1 .LBB0_136
	s_lshl_b32 s2, s56, 1
	v_lshlrev_b32_e32 v2, 1, v4
	s_add_u32 s2, s10, s2
	v_and_b32_e32 v5, 62, v2
	s_addc_u32 s3, s11, 0
	s_lshl_b64 s[6:7], s[56:57], 2
	v_and_b32_e32 v6, 63, v4
	v_lshlrev_b32_e32 v2, 1, v5
	v_mov_b32_e32 v3, v177
	v_ashrrev_i32_e32 v7, 5, v4
	v_ashrrev_i32_e32 v9, 6, v4
	s_waitcnt vmcnt(1)
	v_add_u32_e32 v25, 0x100, v4
	v_add_u32_e32 v27, 0x200, v4
	s_waitcnt vmcnt(0)
	v_add_u32_e32 v29, 0x300, v4
	v_add_u32_e32 v31, 0x400, v4
	v_add_u32_e32 v33, 0x500, v4
	v_add_u32_e32 v35, 0x600, v4
	v_add_u32_e32 v37, 0x700, v4
	v_add_u32_e32 v17, 0x800, v4
	v_add_u32_e32 v18, 0x900, v4
	v_add_u32_e32 v19, 0xa00, v4
	v_add_u32_e32 v20, 0xb00, v4
	v_add_u32_e32 v21, 0xc00, v4
	v_add_u32_e32 v22, 0xd00, v4
	v_add_u32_e32 v23, 0xe00, v4
	v_add_u32_e32 v4, 0xf00, v4
	s_add_u32 s6, s12, s6
	v_lshl_add_u64 v[2:3], s[2:3], 0, v[2:3]
	s_movk_i32 s2, 0x104
	v_ashrrev_i32_e32 v10, 6, v25
	v_ashrrev_i32_e32 v11, 6, v27
	v_ashrrev_i32_e32 v12, 6, v29
	v_ashrrev_i32_e32 v13, 6, v31
	v_ashrrev_i32_e32 v14, 6, v33
	v_ashrrev_i32_e32 v15, 6, v35
	v_ashrrev_i32_e32 v16, 6, v37
	v_ashrrev_i32_e32 v17, 6, v17
	v_ashrrev_i32_e32 v18, 6, v18
	v_ashrrev_i32_e32 v19, 6, v19
	v_ashrrev_i32_e32 v20, 6, v20
	v_ashrrev_i32_e32 v21, 6, v21
	v_ashrrev_i32_e32 v22, 6, v22
	v_ashrrev_i32_e32 v23, 6, v23
	v_ashrrev_i32_e32 v24, 6, v4
	v_ashrrev_i32_e32 v25, 5, v25
	v_ashrrev_i32_e32 v27, 5, v27
	v_ashrrev_i32_e32 v29, 5, v29
	v_ashrrev_i32_e32 v31, 5, v31
	v_ashrrev_i32_e32 v33, 5, v33
	v_ashrrev_i32_e32 v35, 5, v35
	v_ashrrev_i32_e32 v37, 5, v37
	s_addc_u32 s7, s13, s7
	v_lshlrev_b32_e32 v176, 2, v6
	v_lshlrev_b32_e32 v8, 2, v7
	v_mul_lo_u32 v39, v9, s2
	v_mul_lo_u32 v40, v10, s2
	v_mul_lo_u32 v41, v11, s2
	v_mul_lo_u32 v42, v12, s2
	v_mul_lo_u32 v43, v13, s2
	v_mul_lo_u32 v44, v14, s2
	v_mul_lo_u32 v45, v15, s2
	v_mul_lo_u32 v46, v16, s2
	v_mul_lo_u32 v47, v17, s2
	v_mul_lo_u32 v48, v18, s2
	v_mul_lo_u32 v49, v19, s2
	v_mul_lo_u32 v50, v20, s2
	v_mul_lo_u32 v51, v21, s2
	v_mul_lo_u32 v52, v22, s2
	v_mul_lo_u32 v53, v23, s2
	v_mul_lo_u32 v4, v24, s2
	v_lshlrev_b32_e32 v26, 2, v25
	v_lshlrev_b32_e32 v28, 2, v27
	v_lshlrev_b32_e32 v30, 2, v29
	v_lshlrev_b32_e32 v32, 2, v31
	v_lshlrev_b32_e32 v34, 2, v33
	v_lshlrev_b32_e32 v36, 2, v35
	v_lshlrev_b32_e32 v38, 2, v37
	v_lshl_add_u64 v[0:1], s[6:7], 0, v[176:177]
	v_mad_u32_u24 v8, v5, s2, v8
	v_mad_u32_u24 v26, v5, s2, v26
	v_mad_u32_u24 v28, v5, s2, v28
	v_mad_u32_u24 v30, v5, s2, v30
	v_mad_u32_u24 v32, v5, s2, v32
	v_mad_u32_u24 v34, v5, s2, v34
	v_mad_u32_u24 v36, v5, s2, v36
	v_mad_u32_u24 v38, v5, s2, v38
	v_add_u32_e32 v39, v176, v39
	v_add_u32_e32 v40, v176, v40
	v_add_u32_e32 v41, v176, v41
	v_add_u32_e32 v42, v176, v42
	v_add_u32_e32 v43, v176, v43
	v_add_u32_e32 v44, v176, v44
	v_add_u32_e32 v45, v176, v45
	v_add_u32_e32 v46, v176, v46
	v_add_u32_e32 v47, v176, v47
	v_add_u32_e32 v48, v176, v48
	v_add_u32_e32 v49, v176, v49
	v_add_u32_e32 v50, v176, v50
	v_add_u32_e32 v51, v176, v51
	v_add_u32_e32 v52, v176, v52
	v_add_u32_e32 v53, v176, v53
	v_add_u32_e32 v54, v176, v4
	s_branch .LBB0_134

.LBB0_136:
	v_mov_b32_e32 v4, v192
	s_lshl_b32 s17, s16, 3
	s_sub_i32 s17, s55, s17
	s_add_i32 s17, s17, -4
	s_cmp_gt_u32 s17, 3
	s_cbranch_scc1 .LBB0_130
	s_load_dwordx2 s[2:3], s[58:59], 0x48
	s_lshl_b32 s6, s56, 1
	s_add_u32 s6, s14, s6
	s_addc_u32 s7, s15, 0
	s_lshl_b64 s[8:9], s[56:57], 2
	s_waitcnt lgkmcnt(0)
	s_add_u32 s2, s2, s8
	v_and_b32_e32 v6, 63, v4
	s_addc_u32 s3, s3, s9
	v_lshlrev_b32_e32 v176, 2, v6
	v_lshl_add_u64 v[0:1], s[2:3], 0, v[176:177]
	s_mov_b64 s[2:3], 0xa0000
	v_lshlrev_b32_e32 v2, 1, v4
	v_ashrrev_i32_e32 v7, 5, v4
	v_ashrrev_i32_e32 v9, 6, v4
	s_waitcnt vmcnt(1)
	v_add_u32_e32 v25, 0x100, v4
	v_add_u32_e32 v27, 0x200, v4
	s_waitcnt vmcnt(0)
	v_add_u32_e32 v29, 0x300, v4
	v_add_u32_e32 v31, 0x400, v4
	v_add_u32_e32 v33, 0x500, v4
	v_add_u32_e32 v35, 0x600, v4
	v_add_u32_e32 v37, 0x700, v4
	v_add_u32_e32 v17, 0x800, v4
	v_add_u32_e32 v18, 0x900, v4
	v_add_u32_e32 v19, 0xa00, v4
	v_add_u32_e32 v20, 0xb00, v4
	v_add_u32_e32 v21, 0xc00, v4
	v_add_u32_e32 v22, 0xd00, v4
	v_add_u32_e32 v23, 0xe00, v4
	v_add_u32_e32 v4, 0xf00, v4
	v_lshl_add_u64 v[0:1], v[0:1], 0, s[2:3]
	v_and_b32_e32 v5, 62, v2
	s_movk_i32 s2, 0x104
	v_ashrrev_i32_e32 v10, 6, v25
	v_ashrrev_i32_e32 v11, 6, v27
	v_ashrrev_i32_e32 v12, 6, v29
	v_ashrrev_i32_e32 v13, 6, v31
	v_ashrrev_i32_e32 v14, 6, v33
	v_ashrrev_i32_e32 v15, 6, v35
	v_ashrrev_i32_e32 v16, 6, v37
	v_ashrrev_i32_e32 v17, 6, v17
	v_ashrrev_i32_e32 v18, 6, v18
	v_ashrrev_i32_e32 v19, 6, v19
	v_ashrrev_i32_e32 v20, 6, v20
	v_ashrrev_i32_e32 v21, 6, v21
	v_ashrrev_i32_e32 v22, 6, v22
	v_ashrrev_i32_e32 v23, 6, v23
	v_ashrrev_i32_e32 v24, 6, v4
	v_ashrrev_i32_e32 v25, 5, v25
	v_ashrrev_i32_e32 v27, 5, v27
	v_ashrrev_i32_e32 v29, 5, v29
	v_ashrrev_i32_e32 v31, 5, v31
	v_ashrrev_i32_e32 v33, 5, v33
	v_ashrrev_i32_e32 v35, 5, v35
	v_ashrrev_i32_e32 v37, 5, v37
	v_lshlrev_b32_e32 v2, 1, v5
	v_mov_b32_e32 v3, v177
	v_lshlrev_b32_e32 v8, 2, v7
	v_mul_lo_u32 v39, v9, s2
	v_mul_lo_u32 v40, v10, s2
	v_mul_lo_u32 v41, v11, s2
	v_mul_lo_u32 v42, v12, s2
	v_mul_lo_u32 v43, v13, s2
	v_mul_lo_u32 v44, v14, s2
	v_mul_lo_u32 v45, v15, s2
	v_mul_lo_u32 v46, v16, s2
	v_mul_lo_u32 v47, v17, s2
	v_mul_lo_u32 v48, v18, s2
	v_mul_lo_u32 v49, v19, s2
	v_mul_lo_u32 v50, v20, s2
	v_mul_lo_u32 v51, v21, s2
	v_mul_lo_u32 v52, v22, s2
	v_mul_lo_u32 v53, v23, s2
	v_mul_lo_u32 v4, v24, s2
	v_lshlrev_b32_e32 v26, 2, v25
	v_lshlrev_b32_e32 v28, 2, v27
	v_lshlrev_b32_e32 v30, 2, v29
	v_lshlrev_b32_e32 v32, 2, v31
	v_lshlrev_b32_e32 v34, 2, v33
	v_lshlrev_b32_e32 v36, 2, v35
	v_lshlrev_b32_e32 v38, 2, v37
	v_lshl_add_u64 v[2:3], s[6:7], 0, v[2:3]
	v_mad_u32_u24 v8, v5, s2, v8
	v_mad_u32_u24 v26, v5, s2, v26
	v_mad_u32_u24 v28, v5, s2, v28
	v_mad_u32_u24 v30, v5, s2, v30
	v_mad_u32_u24 v32, v5, s2, v32
	v_mad_u32_u24 v34, v5, s2, v34
	v_mad_u32_u24 v36, v5, s2, v36
	v_mad_u32_u24 v38, v5, s2, v38
	v_add_u32_e32 v39, v176, v39
	v_add_u32_e32 v40, v176, v40
	v_add_u32_e32 v41, v176, v41
	v_add_u32_e32 v42, v176, v42
	v_add_u32_e32 v43, v176, v43
	v_add_u32_e32 v44, v176, v44
	v_add_u32_e32 v45, v176, v45
	v_add_u32_e32 v46, v176, v46
	v_add_u32_e32 v47, v176, v47
	v_add_u32_e32 v48, v176, v48
	v_add_u32_e32 v49, v176, v49
	v_add_u32_e32 v50, v176, v50
	v_add_u32_e32 v51, v176, v51
	v_add_u32_e32 v52, v176, v52
	v_add_u32_e32 v53, v176, v53
	v_add_u32_e32 v54, v176, v4
	s_branch .LBB0_139

.LBB0_1505:
	s_lshl_b32 s56, s16, 14
	v_mov_b32_e32 v4, v192
	s_lshl_b32 s17, s16, 3
	s_sub_i32 s17, s55, s17
	s_cmp_gt_u32 s17, 3
	s_cbranch_scc1 .LBB0_1510
	s_lshl_b32 s4, s56, 1
	v_lshlrev_b32_e32 v2, 1, v4
	s_add_u32 s4, s12, s4
	v_and_b32_e32 v5, 62, v2
	s_addc_u32 s5, s13, 0
	s_lshl_b64 s[6:7], s[56:57], 2
	v_and_b32_e32 v6, 63, v4
	v_lshlrev_b32_e32 v2, 1, v5
	v_mov_b32_e32 v3, v177
	v_ashrrev_i32_e32 v7, 5, v4
	v_ashrrev_i32_e32 v9, 6, v4
	s_waitcnt vmcnt(1)
	v_add_u32_e32 v25, 0x100, v4
	v_add_u32_e32 v27, 0x200, v4
	s_waitcnt vmcnt(0)
	v_add_u32_e32 v29, 0x300, v4
	v_add_u32_e32 v31, 0x400, v4
	v_add_u32_e32 v33, 0x500, v4
	v_add_u32_e32 v35, 0x600, v4
	v_add_u32_e32 v37, 0x700, v4
	v_add_u32_e32 v17, 0x800, v4
	v_add_u32_e32 v18, 0x900, v4
	v_add_u32_e32 v19, 0xa00, v4
	v_add_u32_e32 v20, 0xb00, v4
	v_add_u32_e32 v21, 0xc00, v4
	v_add_u32_e32 v22, 0xd00, v4
	v_add_u32_e32 v23, 0xe00, v4
	v_add_u32_e32 v4, 0xf00, v4
	s_add_u32 s6, s2, s6
	v_lshl_add_u64 v[2:3], s[4:5], 0, v[2:3]
	s_movk_i32 s4, 0x104
	v_ashrrev_i32_e32 v10, 6, v25
	v_ashrrev_i32_e32 v11, 6, v27
	v_ashrrev_i32_e32 v12, 6, v29
	v_ashrrev_i32_e32 v13, 6, v31
	v_ashrrev_i32_e32 v14, 6, v33
	v_ashrrev_i32_e32 v15, 6, v35
	v_ashrrev_i32_e32 v16, 6, v37
	v_ashrrev_i32_e32 v17, 6, v17
	v_ashrrev_i32_e32 v18, 6, v18
	v_ashrrev_i32_e32 v19, 6, v19
	v_ashrrev_i32_e32 v20, 6, v20
	v_ashrrev_i32_e32 v21, 6, v21
	v_ashrrev_i32_e32 v22, 6, v22
	v_ashrrev_i32_e32 v23, 6, v23
	v_ashrrev_i32_e32 v24, 6, v4
	v_ashrrev_i32_e32 v25, 5, v25
	v_ashrrev_i32_e32 v27, 5, v27
	v_ashrrev_i32_e32 v29, 5, v29
	v_ashrrev_i32_e32 v31, 5, v31
	v_ashrrev_i32_e32 v33, 5, v33
	v_ashrrev_i32_e32 v35, 5, v35
	v_ashrrev_i32_e32 v37, 5, v37
	s_addc_u32 s7, s3, s7
	v_lshlrev_b32_e32 v176, 2, v6
	v_lshlrev_b32_e32 v8, 2, v7
	v_mul_lo_u32 v39, v9, s4
	v_mul_lo_u32 v40, v10, s4
	v_mul_lo_u32 v41, v11, s4
	v_mul_lo_u32 v42, v12, s4
	v_mul_lo_u32 v43, v13, s4
	v_mul_lo_u32 v44, v14, s4
	v_mul_lo_u32 v45, v15, s4
	v_mul_lo_u32 v46, v16, s4
	v_mul_lo_u32 v47, v17, s4
	v_mul_lo_u32 v48, v18, s4
	v_mul_lo_u32 v49, v19, s4
	v_mul_lo_u32 v50, v20, s4
	v_mul_lo_u32 v51, v21, s4
	v_mul_lo_u32 v52, v22, s4
	v_mul_lo_u32 v53, v23, s4
	v_mul_lo_u32 v4, v24, s4
	v_lshlrev_b32_e32 v26, 2, v25
	v_lshlrev_b32_e32 v28, 2, v27
	v_lshlrev_b32_e32 v30, 2, v29
	v_lshlrev_b32_e32 v32, 2, v31
	v_lshlrev_b32_e32 v34, 2, v33
	v_lshlrev_b32_e32 v36, 2, v35
	v_lshlrev_b32_e32 v38, 2, v37
	v_lshl_add_u64 v[0:1], s[6:7], 0, v[176:177]
	v_mad_u32_u24 v8, v5, s4, v8
	v_mad_u32_u24 v26, v5, s4, v26
	v_mad_u32_u24 v28, v5, s4, v28
	v_mad_u32_u24 v30, v5, s4, v30
	v_mad_u32_u24 v32, v5, s4, v32
	v_mad_u32_u24 v34, v5, s4, v34
	v_mad_u32_u24 v36, v5, s4, v36
	v_mad_u32_u24 v38, v5, s4, v38
	v_add_u32_e32 v39, v176, v39
	v_add_u32_e32 v40, v176, v40
	v_add_u32_e32 v41, v176, v41
	v_add_u32_e32 v42, v176, v42
	v_add_u32_e32 v43, v176, v43
	v_add_u32_e32 v44, v176, v44
	v_add_u32_e32 v45, v176, v45
	v_add_u32_e32 v46, v176, v46
	v_add_u32_e32 v47, v176, v47
	v_add_u32_e32 v48, v176, v48
	v_add_u32_e32 v49, v176, v49
	v_add_u32_e32 v50, v176, v50
	v_add_u32_e32 v51, v176, v51
	v_add_u32_e32 v52, v176, v52
	v_add_u32_e32 v53, v176, v53
	v_add_u32_e32 v54, v176, v4
	s_branch .LBB0_1508

.LBB0_1510:
	v_mov_b32_e32 v4, v192
	s_lshl_b32 s17, s16, 3
	s_sub_i32 s17, s55, s17
	s_add_i32 s17, s17, -4
	s_cmp_gt_u32 s17, 3
	s_cbranch_scc1 .LBB0_1504
	s_load_dwordx2 s[4:5], s[58:59], 0x48
	s_lshl_b32 s6, s56, 1
	s_add_u32 s6, s14, s6
	s_addc_u32 s7, s15, 0
	s_lshl_b64 s[10:11], s[56:57], 2
	s_waitcnt lgkmcnt(0)
	s_add_u32 s4, s4, s10
	v_and_b32_e32 v6, 63, v4
	s_addc_u32 s5, s5, s11
	v_lshlrev_b32_e32 v176, 2, v6
	v_lshlrev_b32_e32 v2, 1, v4
	v_ashrrev_i32_e32 v7, 5, v4
	v_ashrrev_i32_e32 v9, 6, v4
	s_waitcnt vmcnt(1)
	v_add_u32_e32 v25, 0x100, v4
	v_add_u32_e32 v27, 0x200, v4
	s_waitcnt vmcnt(0)
	v_add_u32_e32 v29, 0x300, v4
	v_add_u32_e32 v31, 0x400, v4
	v_add_u32_e32 v33, 0x500, v4
	v_add_u32_e32 v35, 0x600, v4
	v_add_u32_e32 v37, 0x700, v4
	v_add_u32_e32 v17, 0x800, v4
	v_add_u32_e32 v18, 0x900, v4
	v_add_u32_e32 v19, 0xa00, v4
	v_add_u32_e32 v20, 0xb00, v4
	v_add_u32_e32 v21, 0xc00, v4
	v_add_u32_e32 v22, 0xd00, v4
	v_add_u32_e32 v23, 0xe00, v4
	v_add_u32_e32 v4, 0xf00, v4
	v_lshl_add_u64 v[0:1], s[4:5], 0, v[176:177]
	v_and_b32_e32 v5, 62, v2
	s_movk_i32 s4, 0x104
	v_ashrrev_i32_e32 v10, 6, v25
	v_ashrrev_i32_e32 v11, 6, v27
	v_ashrrev_i32_e32 v12, 6, v29
	v_ashrrev_i32_e32 v13, 6, v31
	v_ashrrev_i32_e32 v14, 6, v33
	v_ashrrev_i32_e32 v15, 6, v35
	v_ashrrev_i32_e32 v16, 6, v37
	v_ashrrev_i32_e32 v17, 6, v17
	v_ashrrev_i32_e32 v18, 6, v18
	v_ashrrev_i32_e32 v19, 6, v19
	v_ashrrev_i32_e32 v20, 6, v20
	v_ashrrev_i32_e32 v21, 6, v21
	v_ashrrev_i32_e32 v22, 6, v22
	v_ashrrev_i32_e32 v23, 6, v23
	v_ashrrev_i32_e32 v24, 6, v4
	v_ashrrev_i32_e32 v25, 5, v25
	v_ashrrev_i32_e32 v27, 5, v27
	v_ashrrev_i32_e32 v29, 5, v29
	v_ashrrev_i32_e32 v31, 5, v31
	v_ashrrev_i32_e32 v33, 5, v33
	v_ashrrev_i32_e32 v35, 5, v35
	v_ashrrev_i32_e32 v37, 5, v37
	v_lshlrev_b32_e32 v2, 1, v5
	v_mov_b32_e32 v3, v177
	v_lshlrev_b32_e32 v8, 2, v7
	v_mul_lo_u32 v39, v9, s4
	v_mul_lo_u32 v40, v10, s4
	v_mul_lo_u32 v41, v11, s4
	v_mul_lo_u32 v42, v12, s4
	v_mul_lo_u32 v43, v13, s4
	v_mul_lo_u32 v44, v14, s4
	v_mul_lo_u32 v45, v15, s4
	v_mul_lo_u32 v46, v16, s4
	v_mul_lo_u32 v47, v17, s4
	v_mul_lo_u32 v48, v18, s4
	v_mul_lo_u32 v49, v19, s4
	v_mul_lo_u32 v50, v20, s4
	v_mul_lo_u32 v51, v21, s4
	v_mul_lo_u32 v52, v22, s4
	v_mul_lo_u32 v53, v23, s4
	v_mul_lo_u32 v4, v24, s4
	v_lshlrev_b32_e32 v26, 2, v25
	v_lshlrev_b32_e32 v28, 2, v27
	v_lshlrev_b32_e32 v30, 2, v29
	v_lshlrev_b32_e32 v32, 2, v31
	v_lshlrev_b32_e32 v34, 2, v33
	v_lshlrev_b32_e32 v36, 2, v35
	v_lshlrev_b32_e32 v38, 2, v37
	v_lshl_add_u64 v[2:3], s[6:7], 0, v[2:3]
	v_mad_u32_u24 v8, v5, s4, v8
	v_mad_u32_u24 v26, v5, s4, v26
	v_mad_u32_u24 v28, v5, s4, v28
	v_mad_u32_u24 v30, v5, s4, v30
	v_mad_u32_u24 v32, v5, s4, v32
	v_mad_u32_u24 v34, v5, s4, v34
	v_mad_u32_u24 v36, v5, s4, v36
	v_mad_u32_u24 v38, v5, s4, v38
	v_add_u32_e32 v39, v176, v39
	v_add_u32_e32 v40, v176, v40
	v_add_u32_e32 v41, v176, v41
	v_add_u32_e32 v42, v176, v42
	v_add_u32_e32 v43, v176, v43
	v_add_u32_e32 v44, v176, v44
	v_add_u32_e32 v45, v176, v45
	v_add_u32_e32 v46, v176, v46
	v_add_u32_e32 v47, v176, v47
	v_add_u32_e32 v48, v176, v48
	v_add_u32_e32 v49, v176, v49
	v_add_u32_e32 v50, v176, v50
	v_add_u32_e32 v51, v176, v51
	v_add_u32_e32 v52, v176, v52
	v_add_u32_e32 v53, v176, v53
	v_add_u32_e32 v54, v176, v4
	s_branch .LBB0_1513
